# attention tile loops: one static s_setprio 1 for the leading wave group (waves 0-3) across each tile loop, reset at the join (the trailing-group raise measured clearly worse)
# speedup vs baseline: 1.0038x; 1.0022x over previous
; #define GLOAD(K0, K1, V0, V1, kvt) do { const size_t ko_ = (size_t)(kvt) * 64 * QKVW; const int vo_ = (kvt) * 64; \
;         K0 = *(const u32x4*)(kg0 + ko_); K1 = *(const u32x4*)(kg1 + ko_); V0 = *(const u32x4*)(vg0 + vo_); V1 = *(const u32x4*)(vg1 + vo_); } while (0)
; #define STEP_LEAD(kvt, kslot, vso) do { f32x16 p0, p1; bool act, lval; \
;             QK_TILE(kvt, kslot); \
;             if (act) { SOFTMAX_HALF(p0, pa0, pb0); PV_HALF(vso, 0, pa0, pb0); SOFTMAX_HALF(p1, pa1, pb1); PV_HALF(vso, 2, pa1, pb1); } \
;         } while (0)
; #define STEP_TRAIL(kvt, kslot, vso) do { f32x16 p0, p1; bool act, lval; \
;             if (actp) { PV_HALF(vsp, 0, pa0, pb0); PV_HALF(vsp, 2, pa1, pb1); } \
;             QK_TILE(kvt, kslot); \
;             if (act) { SOFTMAX_FULL(p0, p1, pa0, pb0, pa1, pb1); } \
;             actp = act; vsp = (vso); \
;         } while (0)
; template <int MODE> ...
;     ...
;         mymask = rm[slab * 32 + r32];
;         ntiles = tl[64];
;     } else {
;         ntiles = 2 * qb + 2;
;     }
;     bf16x8 qf[NDK];
;     { const bf16_t* qp = QKV + (tokbase + qpos) * QKVW + qcol + hi * 8;
; #pragma unroll
;       for (int dk = 0; dk < NDK; ++dk) qf[dk] = *(const bf16x8*)(qp + dk * 16); }
;     float m = NEG, l = 0.f;
;     f32x16 o[4];
; #pragma unroll
;     for (int i = 0; i < 4; ++i)
; #pragma unroll
;         for (int r = 0; r < 16; ++r) o[i][r] = 0.f;
;     u32x4 kr0, kr1, vr0, vr1;
;     const int idA = tid, idB = tid + 512;
;     const bf16_t* kg0 = QKV + (tokbase + (idA >> 4)) * QKVW + kcol + (idA & 15) * 8;
;     const bf16_t* kg1 = QKV + (tokbase + (idB >> 4)) * QKVW + kcol + (idB & 15) * 8;
;     const bf16_t* vg0 = VTb + (size_t)(idA >> 3) * SEQ + (idA & 7) * 8;
;     const bf16_t* vg1 = VTb + (size_t)(idB >> 3) * SEQ + (idB & 7) * 8;
;     const int kl0 = (idA >> 4) * KP + (idA & 15) * 16, kl1 = (idB >> 4) * KP + (idB & 15) * 16;
;     const int vl0 = VRING + (idA >> 3) * VP + ((idA & 7) >> 1) * 32 + (idA & 1) * 8, vl1 = VRING + (idB >> 3) * VP + ((idB & 7) >> 1) * 32 + (idB & 1) * 8;
;     ...
;     GLOAD(kr0, kr1, vr0, vr1, TILE_AT(0));
;     if (trailing) {
;         TILE_LOOP(STEP_TRAIL);
;         if (actp) { PV_HALF(vsp, 0, pa0, pb0); PV_HALF(vsp, 2, pa1, pb1); }
;     } else {
;         TILE_LOOP(STEP_LEAD);
.LBB0_156:
	s_or_b64 exec, exec, s[4:5]
	s_ashr_i32 s7, s45, 6
	s_lshl_b32 s4, s0, 8
	s_lshl_b32 s74, s7, 5
	s_add_i32 s74, s74, s4
	s_add_i32 s4, s44, s24
	v_and_b32_e32 v186, 31, v8
	s_add_i32 s4, s4, 32
	s_lshl_b32 s1, s24, 7
	v_or_b32_e32 v168, s74, v186
	s_ashr_i32 s5, s4, 31
	s_or_b32 s6, s1, 0xc00
	s_or_b32 s8, s1, 0x1000
	s_lshl_b64 s[4:5], s[4:5], 20
	v_ashrrev_i32_e32 v169, 31, v168
	s_add_u32 s54, s76, s4
	v_lshl_add_u64 v[166:167], s[14:15], 0, v[168:169]
	v_mov_b64_e32 v[0:1], s[68:69]
	s_addc_u32 s55, s77, s5
	v_mad_u64_u32 v[2:3], s[4:5], v166, s35, v[0:1]
	v_bfe_u32 v185, v8, 5, 1
	v_mad_i32_i24 v3, v167, s35, v3
	s_lshl_b32 s24, s6, 1
	v_lshl_add_u64 v[2:3], v[2:3], 0, s[24:25]
	v_lshlrev_b32_e32 v160, 4, v185
	v_lshl_add_u64 v[2:3], v[2:3], 0, v[160:161]
	s_waitcnt lgkmcnt(0)
	s_barrier
	global_load_dwordx4 v[96:99], v[2:3], off
	global_load_dwordx4 v[100:103], v[2:3], off offset:32
	global_load_dwordx4 v[104:107], v[2:3], off offset:64
	global_load_dwordx4 v[108:111], v[2:3], off offset:96
	global_load_dwordx4 v[112:115], v[2:3], off offset:128
	global_load_dwordx4 v[116:119], v[2:3], off offset:160
	global_load_dwordx4 v[120:123], v[2:3], off offset:192
	global_load_dwordx4 v[124:127], v[2:3], off offset:224
	v_ashrrev_i32_e32 v2, 4, v8
	v_ashrrev_i32_e32 v3, 31, v2
	v_lshl_add_u64 v[4:5], s[14:15], 0, v[2:3]
	v_mad_u64_u32 v[6:7], s[4:5], v4, s35, v[0:1]
	v_mad_i32_i24 v7, v5, s35, v7
	s_lshl_b32 s78, s8, 1
	s_mov_b32 s79, s25
	v_lshlrev_b32_e32 v3, 4, v8
	v_add_u32_e32 v14, 0x200, v8
	v_lshl_add_u64 v[4:5], v[6:7], 0, s[78:79]
	v_and_b32_e32 v6, 0xf0, v3
	v_mov_b32_e32 v7, v161
	v_lshl_add_u64 v[170:171], v[4:5], 0, v[6:7]
	v_ashrrev_i32_e32 v4, 4, v14
	v_ashrrev_i32_e32 v5, 31, v4
	v_lshl_add_u64 v[10:11], s[14:15], 0, v[4:5]
	v_mad_u64_u32 v[0:1], s[4:5], v10, s35, v[0:1]
	v_mad_i32_i24 v1, v11, s35, v1
	v_lshl_add_u64 v[0:1], v[0:1], 0, s[78:79]
	v_lshl_add_u64 v[172:173], v[0:1], 0, v[6:7]
	v_ashrrev_i32_e32 v0, 3, v8
	v_ashrrev_i32_e32 v1, 31, v0
	v_lshlrev_b64 v[10:11], 13, v[0:1]
	v_and_b32_e32 v1, 7, v8
	v_readlane_b32 s4, v254, 8
	v_lshlrev_b32_e32 v12, 4, v1
	v_lshl_add_u64 v[10:11], s[54:55], 0, v[10:11]
	v_mov_b32_e32 v1, s4
	v_mov_b32_e32 v13, v161
	ds_read_b32 v1, v1
	v_lshl_add_u64 v[174:175], v[10:11], 0, v[12:13]
	v_ashrrev_i32_e32 v10, 3, v14
	v_ashrrev_i32_e32 v11, 31, v10
	v_lshlrev_b64 v[14:15], 13, v[10:11]
	v_lshl_add_u64 v[14:15], s[54:55], 0, v[14:15]
	v_lshl_add_u64 v[176:177], v[14:15], 0, v[12:13]
	s_waitcnt lgkmcnt(0)
	v_lshlrev_b32_e32 v12, 6, v1
	v_ashrrev_i32_e32 v13, 31, v12
	v_lshlrev_b64 v[12:13], 1, v[12:13]
	v_mad_i64_i32 v[14:15], s[4:5], v1, s22, v[170:171]
	v_mad_i64_i32 v[16:17], s[4:5], v1, s22, v[172:173]
	global_load_dwordx4 v[128:131], v[14:15], off
	global_load_dwordx4 v[132:135], v[16:17], off
	v_lshl_add_u64 v[14:15], v[174:175], 0, v[12:13]
	v_lshl_add_u64 v[12:13], v[176:177], 0, v[12:13]
	global_load_dwordx4 v[140:143], v[14:15], off
	global_load_dwordx4 v[136:139], v[12:13], off
	v_readlane_b32 s5, v254, 9
	s_lshl_b32 s4, s7, 7
	s_add_i32 s4, s4, 0
	v_mov_b32_e32 v1, s5
	ds_read_b32 v1, v1
	v_lshl_add_u32 v5, v186, 2, s4
	v_add_u32_e32 v5, 0x1c000, v5
	ds_read_b32 v169, v5
	v_mad_u64_u32 v[180:181], s[4:5], v4, s49, v[6:7]
	v_mul_lo_u32 v181, v0, s23
	v_and_b32_e32 v187, 0x60, v3
	v_lshlrev_b32_e32 v0, 3, v8
	s_waitcnt lgkmcnt(1)
	v_cmp_lt_i32_e32 vcc, 0, v1
	v_mad_u64_u32 v[178:179], s[4:5], v2, s49, v[6:7]
	v_and_or_b32 v190, v0, 8, v187
	v_cndmask_b32_e64 v0, 0, 1, vcc
	v_readfirstlane_b32 s75, v1
	v_lshlrev_b32_e32 v188, 3, v9
	v_mul_lo_u32 v189, v10, s23
	s_cmp_gt_i32 s7, 3
	s_mov_b64 s[4:5], -1
	v_cmp_ne_u32_e64 s[6:7], 1, v0
	s_cbranch_scc1 .LBB0_174
	s_and_b64 vcc, exec, s[6:7]
	s_cbranch_vccnz .LBB0_192
	v_mov_b32_e32 v14, v161
	v_mov_b32_e32 v15, v161
	v_mov_b32_e32 v0, v161
	v_mov_b32_e32 v1, v161
	v_mov_b32_e32 v2, v161
	v_mov_b32_e32 v3, v161
	v_mov_b32_e32 v4, v161
	v_mov_b32_e32 v5, v161
	v_mov_b32_e32 v6, v161
	v_mov_b32_e32 v7, v161
	v_mov_b32_e32 v8, v161
	v_mov_b32_e32 v9, v161
	v_mov_b32_e32 v10, v161
	v_mov_b32_e32 v11, v161
	v_mov_b32_e32 v12, v161
	v_mov_b32_e32 v13, v161
	v_mov_b64_e32 v[30:31], v[14:15]
	v_mov_b64_e32 v[62:63], v[14:15]
	v_mov_b64_e32 v[46:47], v[14:15]
	s_waitcnt vmcnt(3)
	v_mov_b64_e32 v[150:151], v[130:131]
	s_waitcnt vmcnt(2)
	v_mov_b64_e32 v[154:155], v[134:135]
	s_waitcnt vmcnt(1)
	v_mov_b64_e32 v[158:159], v[142:143]
	s_waitcnt vmcnt(0)
	v_mov_b64_e32 v[146:147], v[138:139]
	s_add_i32 s28, s75, -1
	s_or_b32 s29, s74, 31
	v_mul_u32_u24_e32 v191, 0x110, v186
	v_lshlrev_b32_e32 v192, 2, v185
	v_mul_u32_u24_e32 v193, 0x90, v186
	v_add3_u32 v194, v181, v188, v187
	s_add_i32 s79, 0, 0x1c400
	v_add_u32_e32 v195, v190, v189
	s_mov_b32 s86, 0
	v_mov_b32_e32 v179, 0
	v_mov_b32_e32 v182, 0xf149f2ca
	v_mov_b64_e32 v[28:29], v[12:13]
	v_mov_b64_e32 v[26:27], v[10:11]
	v_mov_b64_e32 v[24:25], v[8:9]
	v_mov_b64_e32 v[22:23], v[6:7]
	v_mov_b64_e32 v[20:21], v[4:5]
	v_mov_b64_e32 v[18:19], v[2:3]
	v_mov_b64_e32 v[16:17], v[0:1]
	v_mov_b64_e32 v[60:61], v[12:13]
	v_mov_b64_e32 v[58:59], v[10:11]
	v_mov_b64_e32 v[56:57], v[8:9]
	v_mov_b64_e32 v[54:55], v[6:7]
	v_mov_b64_e32 v[52:53], v[4:5]
	v_mov_b64_e32 v[50:51], v[2:3]
	v_mov_b64_e32 v[48:49], v[0:1]
	v_mov_b64_e32 v[44:45], v[12:13]
	v_mov_b64_e32 v[42:43], v[10:11]
	v_mov_b64_e32 v[40:41], v[8:9]
	v_mov_b64_e32 v[38:39], v[6:7]
	v_mov_b64_e32 v[36:37], v[4:5]
	v_mov_b64_e32 v[34:35], v[2:3]
	v_mov_b64_e32 v[32:33], v[0:1]
	v_mov_b64_e32 v[148:149], v[128:129]
	v_mov_b64_e32 v[152:153], v[132:133]
	v_mov_b64_e32 v[156:157], v[140:141]
	v_mov_b64_e32 v[144:145], v[136:137]
	s_mov_b32 s87, 0
	s_mov_b32 s88, 0
	s_setprio 1
	s_branch .LBB0_161

; #define LAS __attribute__((address_space(3)))
; __device__ __forceinline__ unsigned pk2(float lo, float hi) { const f32x2 v = {lo, hi}; const bf16x2_cv b = __builtin_convertvector(v, bf16x2_cv); return __builtin_bit_cast(unsigned, b); }
; #define LAS __attribute__((address_space(3)))
; __device__ __forceinline__ unsigned pk2(float lo, float hi) { return f2bf(lo) | (f2bf(hi) << 16); }
; template <int MODE> ...
;     ...
;         ((LAS f32x4*)km)[tid] = ((const f32x4*)(kmean + (size_t)(b * 8 + h) * 16 * 128))[tid];
;         if (tid == 0) tl[65] = 0;
;     ...
;     l += __shfl_xor(l, 32);
;     const float inv = 1.0f / l;
;     if (MODE == 1) {
;         bf16_t* yp = Y + (tokbase + qpos) * 1024 + h * 128 + 4 * hi;
; #pragma unroll
;         for (int bl = 0; bl < 4; ++bl)
; #pragma unroll
;             for (int g = 0; g < 4; ++g) {
;                 u32x2 w; w.x = pk2(o[bl][4 * g] * inv, o[bl][4 * g + 1] * inv); w.y = pk2(o[bl][4 * g + 2] * inv, o[bl][4 * g + 3] * inv);
;                 *(u32x2*)(yp + bl * 32 + 8 * g) = w;
;             }
;         __syncthreads();
.LBB0_196:
	s_setprio 0
	ds_bpermute_b32 v64, v163, v179
	s_lshl_b32 s44, s1, 1
	s_mov_b32 s45, s25
	v_lshlrev_b32_e32 v160, 3, v185
	s_waitcnt lgkmcnt(0)
	v_add_f32_e32 v64, v179, v64
	v_div_scale_f32 v65, s[4:5], v64, v64, 1.0
	v_rcp_f32_e32 v66, v65
	s_nop 0
	v_fma_f32 v67, -v65, v66, 1.0
	v_fmac_f32_e32 v66, v67, v66
	v_div_scale_f32 v67, vcc, 1.0, v64, 1.0
	v_mul_f32_e32 v68, v67, v66
	v_fma_f32 v69, -v65, v68, v67
	v_fmac_f32_e32 v68, v69, v66
	v_fma_f32 v65, -v65, v68, v67
	v_div_fmas_f32 v65, v65, v66, v68
	v_lshlrev_b64 v[66:67], 11, v[166:167]
	v_div_fixup_f32 v64, v65, v64, 1.0
	v_lshl_add_u64 v[66:67], s[10:11], 0, v[66:67]
	v_lshl_add_u64 v[66:67], v[66:67], 0, s[44:45]
	v_pk_mul_f32 v[32:33], v[32:33], v[64:65] op_sel_hi:[1,0]
	v_pk_mul_f32 v[34:35], v[34:35], v[64:65] op_sel_hi:[1,0]
	v_lshl_add_u64 v[66:67], v[66:67], 0, v[160:161]
	v_cvt_pk_bf16_f32 v32, v32, v33
	v_cvt_pk_bf16_f32 v33, v34, v35
	global_store_dwordx2 v[66:67], v[32:33], off
	v_pk_mul_f32 v[32:33], v[36:37], v[64:65] op_sel_hi:[1,0]
	v_pk_mul_f32 v[34:35], v[38:39], v[64:65] op_sel_hi:[1,0]
	v_cvt_pk_bf16_f32 v32, v32, v33
	v_cvt_pk_bf16_f32 v33, v34, v35
	global_store_dwordx2 v[66:67], v[32:33], off offset:16
	v_pk_mul_f32 v[32:33], v[40:41], v[64:65] op_sel_hi:[1,0]
	v_pk_mul_f32 v[34:35], v[42:43], v[64:65] op_sel_hi:[1,0]
	v_cvt_pk_bf16_f32 v32, v32, v33
	v_cvt_pk_bf16_f32 v33, v34, v35
	global_store_dwordx2 v[66:67], v[32:33], off offset:32
	v_pk_mul_f32 v[32:33], v[44:45], v[64:65] op_sel_hi:[1,0]
	v_pk_mul_f32 v[34:35], v[46:47], v[64:65] op_sel_hi:[1,0]
	v_cvt_pk_bf16_f32 v32, v32, v33
	v_cvt_pk_bf16_f32 v33, v34, v35
	global_store_dwordx2 v[66:67], v[32:33], off offset:48
	v_pk_mul_f32 v[32:33], v[48:49], v[64:65] op_sel_hi:[1,0]
	v_pk_mul_f32 v[34:35], v[50:51], v[64:65] op_sel_hi:[1,0]
	v_pk_mul_f32 v[16:17], v[16:17], v[64:65] op_sel_hi:[1,0]
	v_pk_mul_f32 v[18:19], v[18:19], v[64:65] op_sel_hi:[1,0]
	v_pk_mul_f32 v[0:1], v[0:1], v[64:65] op_sel_hi:[1,0]
	v_pk_mul_f32 v[2:3], v[2:3], v[64:65] op_sel_hi:[1,0]
	v_cvt_pk_bf16_f32 v32, v32, v33
	v_cvt_pk_bf16_f32 v33, v34, v35
	v_cvt_pk_bf16_f32 v16, v16, v17
	v_cvt_pk_bf16_f32 v17, v18, v19
	v_cvt_pk_bf16_f32 v0, v0, v1
	v_cvt_pk_bf16_f32 v1, v2, v3
	global_store_dwordx2 v[66:67], v[32:33], off offset:64
	v_pk_mul_f32 v[32:33], v[52:53], v[64:65] op_sel_hi:[1,0]
	v_pk_mul_f32 v[34:35], v[54:55], v[64:65] op_sel_hi:[1,0]
	global_store_dwordx2 v[66:67], v[16:17], off offset:128
	v_pk_mul_f32 v[16:17], v[20:21], v[64:65] op_sel_hi:[1,0]
	v_pk_mul_f32 v[18:19], v[22:23], v[64:65] op_sel_hi:[1,0]
	global_store_dwordx2 v[66:67], v[0:1], off offset:192
	v_pk_mul_f32 v[0:1], v[4:5], v[64:65] op_sel_hi:[1,0]
	v_pk_mul_f32 v[2:3], v[6:7], v[64:65] op_sel_hi:[1,0]
	v_cvt_pk_bf16_f32 v32, v32, v33
	v_cvt_pk_bf16_f32 v33, v34, v35
	v_cvt_pk_bf16_f32 v16, v16, v17
	v_cvt_pk_bf16_f32 v17, v18, v19
	v_cvt_pk_bf16_f32 v0, v0, v1
	v_cvt_pk_bf16_f32 v1, v2, v3
	global_store_dwordx2 v[66:67], v[32:33], off offset:80
	v_pk_mul_f32 v[32:33], v[56:57], v[64:65] op_sel_hi:[1,0]
	v_pk_mul_f32 v[34:35], v[58:59], v[64:65] op_sel_hi:[1,0]
	global_store_dwordx2 v[66:67], v[16:17], off offset:144
	v_pk_mul_f32 v[16:17], v[24:25], v[64:65] op_sel_hi:[1,0]
	v_pk_mul_f32 v[18:19], v[26:27], v[64:65] op_sel_hi:[1,0]
	global_store_dwordx2 v[66:67], v[0:1], off offset:208
	v_pk_mul_f32 v[0:1], v[8:9], v[64:65] op_sel_hi:[1,0]
	v_pk_mul_f32 v[2:3], v[10:11], v[64:65] op_sel_hi:[1,0]
	v_cvt_pk_bf16_f32 v32, v32, v33
	v_cvt_pk_bf16_f32 v33, v34, v35
	v_cvt_pk_bf16_f32 v16, v16, v17
	v_cvt_pk_bf16_f32 v17, v18, v19
	v_cvt_pk_bf16_f32 v0, v0, v1
	v_cvt_pk_bf16_f32 v1, v2, v3
	global_store_dwordx2 v[66:67], v[32:33], off offset:96
	v_pk_mul_f32 v[32:33], v[60:61], v[64:65] op_sel_hi:[1,0]
	v_pk_mul_f32 v[34:35], v[62:63], v[64:65] op_sel_hi:[1,0]
	global_store_dwordx2 v[66:67], v[16:17], off offset:160
	v_pk_mul_f32 v[16:17], v[28:29], v[64:65] op_sel_hi:[1,0]
	v_pk_mul_f32 v[18:19], v[30:31], v[64:65] op_sel_hi:[1,0]
	global_store_dwordx2 v[66:67], v[0:1], off offset:224
	v_pk_mul_f32 v[0:1], v[12:13], v[64:65] op_sel_hi:[1,0]
	v_pk_mul_f32 v[2:3], v[14:15], v[64:65] op_sel_hi:[1,0]
	v_cvt_pk_bf16_f32 v32, v32, v33
	v_cvt_pk_bf16_f32 v33, v34, v35
	v_cvt_pk_bf16_f32 v16, v16, v17
	v_cvt_pk_bf16_f32 v17, v18, v19
	v_cvt_pk_bf16_f32 v0, v0, v1
	v_cvt_pk_bf16_f32 v1, v2, v3
	v_mov_b32_e32 v8, v202
	global_store_dwordx2 v[66:67], v[32:33], off offset:112
	global_store_dwordx2 v[66:67], v[16:17], off offset:176
	global_store_dwordx2 v[66:67], v[0:1], off offset:240
	s_barrier
	s_nop 0
	v_ashrrev_i32_e32 v9, 31, v8
	v_lshl_add_u64 v[0:1], v[8:9], 4, s[80:81]
	global_load_dwordx4 v[0:3], v[0:1], off
	v_lshl_add_u32 v4, v8, 4, 0
	v_readfirstlane_b32 s45, v8
	v_add_u32_e32 v4, 0x1a000, v4
	v_cmp_eq_u32_e32 vcc, 0, v8
	s_waitcnt vmcnt(0)
	ds_write_b128 v4, v[0:3]
	s_and_saveexec_b64 s[4:5], vcc
	s_cbranch_execz .LBB0_198
	v_readlane_b32 s6, v254, 7
	s_nop 1
	v_mov_b32_e32 v0, s6
	ds_write_b32 v0, v161

; #define GLOAD(K0, K1, V0, V1, kvt) do { const size_t ko_ = (size_t)(kvt) * 64 * QKVW; const int vo_ = (kvt) * 64; \
;         K0 = *(const u32x4*)(kg0 + ko_); K1 = *(const u32x4*)(kg1 + ko_); V0 = *(const u32x4*)(vg0 + vo_); V1 = *(const u32x4*)(vg1 + vo_); } while (0)
; #define STEP_LEAD(kvt, kslot, vso) do { f32x16 p0, p1; bool act, lval; \
;             QK_TILE(kvt, kslot); \
;             if (act) { SOFTMAX_HALF(p0, pa0, pb0); PV_HALF(vso, 0, pa0, pb0); SOFTMAX_HALF(p1, pa1, pb1); PV_HALF(vso, 2, pa1, pb1); } \
;         } while (0)
; #define STEP_TRAIL(kvt, kslot, vso) do { f32x16 p0, p1; bool act, lval; \
;             if (actp) { PV_HALF(vsp, 0, pa0, pb0); PV_HALF(vsp, 2, pa1, pb1); } \
;             QK_TILE(kvt, kslot); \
;             if (act) { SOFTMAX_FULL(p0, p1, pa0, pb0, pa1, pb1); } \
;             actp = act; vsp = (vso); \
;         } while (0)
; template <int MODE> ...
;     ...
;         mymask = rm[slab * 32 + r32];
;         ntiles = tl[64];
;     } else {
;         ntiles = 2 * qb + 2;
;     }
;     bf16x8 qf[NDK];
;     { const bf16_t* qp = QKV + (tokbase + qpos) * QKVW + qcol + hi * 8;
; #pragma unroll
;       for (int dk = 0; dk < NDK; ++dk) qf[dk] = *(const bf16x8*)(qp + dk * 16); }
;     float m = NEG, l = 0.f;
;     f32x16 o[4];
; #pragma unroll
;     for (int i = 0; i < 4; ++i)
; #pragma unroll
;         for (int r = 0; r < 16; ++r) o[i][r] = 0.f;
;     u32x4 kr0, kr1, vr0, vr1;
;     const int idA = tid, idB = tid + 512;
;     const bf16_t* kg0 = QKV + (tokbase + (idA >> 4)) * QKVW + kcol + (idA & 15) * 8;
;     const bf16_t* kg1 = QKV + (tokbase + (idB >> 4)) * QKVW + kcol + (idB & 15) * 8;
;     const bf16_t* vg0 = VTb + (size_t)(idA >> 3) * SEQ + (idA & 7) * 8;
;     const bf16_t* vg1 = VTb + (size_t)(idB >> 3) * SEQ + (idB & 7) * 8;
;     const int kl0 = (idA >> 4) * KP + (idA & 15) * 16, kl1 = (idB >> 4) * KP + (idB & 15) * 16;
;     const int vl0 = VRING + (idA >> 3) * VP + ((idA & 7) >> 1) * 32 + (idA & 1) * 8, vl1 = VRING + (idB >> 3) * VP + ((idB & 7) >> 1) * 32 + (idB & 1) * 8;
;     ...
;     GLOAD(kr0, kr1, vr0, vr1, TILE_AT(0));
;     if (trailing) {
;         TILE_LOOP(STEP_TRAIL);
;         if (actp) { PV_HALF(vsp, 0, pa0, pb0); PV_HALF(vsp, 2, pa1, pb1); }
;     } else {
;         TILE_LOOP(STEP_LEAD);
.LBB0_217:
	s_or_b64 exec, exec, s[4:5]
	s_ashr_i32 s6, s45, 6
	s_lshl_b32 s45, s6, 5
	v_and_b32_e32 v186, 31, v8
	s_add_i32 s45, s45, s75
	v_or_b32_e32 v168, s45, v186
	v_ashrrev_i32_e32 v169, 31, v168
	v_lshl_add_u64 v[166:167], s[14:15], 0, v[168:169]
	v_mov_b64_e32 v[0:1], s[68:69]
	v_mad_u64_u32 v[2:3], s[4:5], v166, s35, v[0:1]
	v_bfe_u32 v185, v8, 5, 1
	v_mad_i32_i24 v3, v167, s35, v3
	v_lshl_add_u64 v[2:3], v[2:3], 0, s[24:25]
	v_lshlrev_b32_e32 v160, 4, v185
	v_lshl_add_u64 v[2:3], v[2:3], 0, v[160:161]
	s_waitcnt lgkmcnt(0)
	s_barrier
	global_load_dwordx4 v[96:99], v[2:3], off
	global_load_dwordx4 v[100:103], v[2:3], off offset:32
	global_load_dwordx4 v[104:107], v[2:3], off offset:64
	global_load_dwordx4 v[108:111], v[2:3], off offset:96
	global_load_dwordx4 v[112:115], v[2:3], off offset:128
	global_load_dwordx4 v[116:119], v[2:3], off offset:160
	global_load_dwordx4 v[120:123], v[2:3], off offset:192
	global_load_dwordx4 v[124:127], v[2:3], off offset:224
	v_ashrrev_i32_e32 v2, 4, v8
	v_ashrrev_i32_e32 v3, 31, v2
	v_lshl_add_u64 v[4:5], s[14:15], 0, v[2:3]
	v_mad_u64_u32 v[6:7], s[4:5], v4, s35, v[0:1]
	v_mad_i32_i24 v7, v5, s35, v7
	s_mov_b32 s79, s25
	v_lshlrev_b32_e32 v3, 4, v8
	v_add_u32_e32 v14, 0x200, v8
	v_lshl_add_u64 v[4:5], v[6:7], 0, s[78:79]
	v_and_b32_e32 v6, 0xf0, v3
	v_mov_b32_e32 v7, v161
	v_lshl_add_u64 v[170:171], v[4:5], 0, v[6:7]
	v_ashrrev_i32_e32 v4, 4, v14
	v_ashrrev_i32_e32 v5, 31, v4
	v_lshl_add_u64 v[10:11], s[14:15], 0, v[4:5]
	v_mad_u64_u32 v[0:1], s[4:5], v10, s35, v[0:1]
	v_mad_i32_i24 v1, v11, s35, v1
	v_lshl_add_u64 v[0:1], v[0:1], 0, s[78:79]
	v_lshl_add_u64 v[172:173], v[0:1], 0, v[6:7]
	v_ashrrev_i32_e32 v0, 3, v8
	v_ashrrev_i32_e32 v1, 31, v0
	v_lshlrev_b64 v[10:11], 13, v[0:1]
	v_and_b32_e32 v1, 7, v8
	v_readlane_b32 s4, v254, 8
	v_lshlrev_b32_e32 v12, 4, v1
	v_lshl_add_u64 v[10:11], s[54:55], 0, v[10:11]
	v_mov_b32_e32 v1, s4
	v_mov_b32_e32 v13, v161
	ds_read_b32 v1, v1
	v_lshl_add_u64 v[174:175], v[10:11], 0, v[12:13]
	v_ashrrev_i32_e32 v10, 3, v14
	v_ashrrev_i32_e32 v11, 31, v10
	v_lshlrev_b64 v[14:15], 13, v[10:11]
	v_lshl_add_u64 v[14:15], s[54:55], 0, v[14:15]
	v_lshl_add_u64 v[176:177], v[14:15], 0, v[12:13]
	s_waitcnt lgkmcnt(0)
	v_lshlrev_b32_e32 v12, 6, v1
	v_ashrrev_i32_e32 v13, 31, v12
	v_lshlrev_b64 v[12:13], 1, v[12:13]
	v_mad_i64_i32 v[14:15], s[4:5], v1, s22, v[170:171]
	v_mad_i64_i32 v[16:17], s[4:5], v1, s22, v[172:173]
	global_load_dwordx4 v[128:131], v[14:15], off
	global_load_dwordx4 v[132:135], v[16:17], off
	v_lshl_add_u64 v[14:15], v[174:175], 0, v[12:13]
	v_lshl_add_u64 v[12:13], v[176:177], 0, v[12:13]
	global_load_dwordx4 v[140:143], v[14:15], off
	global_load_dwordx4 v[136:139], v[12:13], off
	v_readlane_b32 s5, v254, 9
	s_lshl_b32 s4, s6, 7
	s_add_i32 s4, s4, 0
	v_mov_b32_e32 v1, s5
	ds_read_b32 v1, v1
	v_lshl_add_u32 v5, v186, 2, s4
	v_add_u32_e32 v5, 0x1c000, v5
	ds_read_b32 v169, v5
	v_mad_u64_u32 v[180:181], s[4:5], v4, s49, v[6:7]
	v_mul_lo_u32 v181, v0, s23
	v_and_b32_e32 v187, 0x60, v3
	v_lshlrev_b32_e32 v0, 3, v8
	s_waitcnt lgkmcnt(1)
	v_cmp_lt_i32_e32 vcc, 0, v1
	v_mad_u64_u32 v[178:179], s[4:5], v2, s49, v[6:7]
	v_and_or_b32 v190, v0, 8, v187
	v_cndmask_b32_e64 v0, 0, 1, vcc
	v_readfirstlane_b32 s24, v1
	v_lshlrev_b32_e32 v188, 3, v9
	v_mul_lo_u32 v189, v10, s23
	s_cmp_gt_i32 s6, 3
	s_mov_b64 s[4:5], -1
	v_cmp_ne_u32_e64 s[6:7], 1, v0
	s_cbranch_scc1 .LBB0_235
	s_and_b64 vcc, exec, s[6:7]
	s_cbranch_vccnz .LBB0_253
	v_mov_b32_e32 v14, v161
	v_mov_b32_e32 v15, v161
	v_mov_b32_e32 v0, v161
	v_mov_b32_e32 v1, v161
	v_mov_b32_e32 v2, v161
	v_mov_b32_e32 v3, v161
	v_mov_b32_e32 v4, v161
	v_mov_b32_e32 v5, v161
	v_mov_b32_e32 v6, v161
	v_mov_b32_e32 v7, v161
	v_mov_b32_e32 v8, v161
	v_mov_b32_e32 v9, v161
	v_mov_b32_e32 v10, v161
	v_mov_b32_e32 v11, v161
	v_mov_b32_e32 v12, v161
	v_mov_b32_e32 v13, v161
	v_mov_b64_e32 v[30:31], v[14:15]
	v_mov_b64_e32 v[62:63], v[14:15]
	v_mov_b64_e32 v[46:47], v[14:15]
	s_waitcnt vmcnt(3)
	v_mov_b64_e32 v[150:151], v[130:131]
	s_waitcnt vmcnt(2)
	v_mov_b64_e32 v[154:155], v[134:135]
	s_waitcnt vmcnt(1)
	v_mov_b64_e32 v[158:159], v[142:143]
	s_waitcnt vmcnt(0)
	v_mov_b64_e32 v[146:147], v[138:139]
	s_add_i32 s28, s24, -1
	s_or_b32 s29, s45, 31
	v_mul_u32_u24_e32 v191, 0x110, v186
	v_lshlrev_b32_e32 v192, 2, v185
	v_mul_u32_u24_e32 v193, 0x90, v186
	v_add3_u32 v194, v181, v188, v187
	s_add_i32 s54, 0, 0x1c400
	v_add_u32_e32 v195, v190, v189
	s_mov_b32 s55, 0
	v_mov_b32_e32 v179, 0
	v_mov_b32_e32 v182, 0xf149f2ca
	v_mov_b64_e32 v[28:29], v[12:13]
	v_mov_b64_e32 v[26:27], v[10:11]
	v_mov_b64_e32 v[24:25], v[8:9]
	v_mov_b64_e32 v[22:23], v[6:7]
	v_mov_b64_e32 v[20:21], v[4:5]
	v_mov_b64_e32 v[18:19], v[2:3]
	v_mov_b64_e32 v[16:17], v[0:1]
	v_mov_b64_e32 v[60:61], v[12:13]
	v_mov_b64_e32 v[58:59], v[10:11]
	v_mov_b64_e32 v[56:57], v[8:9]
	v_mov_b64_e32 v[54:55], v[6:7]
	v_mov_b64_e32 v[52:53], v[4:5]
	v_mov_b64_e32 v[50:51], v[2:3]
	v_mov_b64_e32 v[48:49], v[0:1]
	v_mov_b64_e32 v[44:45], v[12:13]
	v_mov_b64_e32 v[42:43], v[10:11]
	v_mov_b64_e32 v[40:41], v[8:9]
	v_mov_b64_e32 v[38:39], v[6:7]
	v_mov_b64_e32 v[36:37], v[4:5]
	v_mov_b64_e32 v[34:35], v[2:3]
	v_mov_b64_e32 v[32:33], v[0:1]
	v_mov_b64_e32 v[148:149], v[128:129]
	v_mov_b64_e32 v[152:153], v[132:133]
	v_mov_b64_e32 v[156:157], v[140:141]
	v_mov_b64_e32 v[144:145], v[136:137]
	s_mov_b32 s75, 0
	s_mov_b32 s78, 0
	s_setprio 1
	s_branch .LBB0_222

; __device__ __forceinline__ unsigned pk2(float lo, float hi) { const f32x2 v = {lo, hi}; const bf16x2_cv b = __builtin_convertvector(v, bf16x2_cv); return __builtin_bit_cast(unsigned, b); }
; __device__ __forceinline__ unsigned pk2(float lo, float hi) { return f2bf(lo) | (f2bf(hi) << 16); }
; template <int MODE> ...
;     ...
;     l += __shfl_xor(l, 32);
;     const float inv = 1.0f / l;
;     if (MODE == 1) {
;         bf16_t* yp = Y + (tokbase + qpos) * 1024 + h * 128 + 4 * hi;
; #pragma unroll
;         for (int bl = 0; bl < 4; ++bl)
; #pragma unroll
;             for (int g = 0; g < 4; ++g) {
;                 u32x2 w; w.x = pk2(o[bl][4 * g] * inv, o[bl][4 * g + 1] * inv); w.y = pk2(o[bl][4 * g + 2] * inv, o[bl][4 * g + 3] * inv);
;                 *(u32x2*)(yp + bl * 32 + 8 * g) = w;
;             }
;         __syncthreads();
; __global__ void __launch_bounds__(NTHR, 2) fwd_kernel(Params P) {
;     ...
; #pragma unroll 1
;                     for (int i = 0; i < 4; ++i) {
;                         const int qb = i == 0 ? s : i == 1 ? 15 - s : i == 2 ? 16 + s : 31 - s;
;                         att::attn_unit<0>(lds, QKV, VT, nullptr, YA, b, hh, qb, lam, 1.0f - linit, Pp->in[I_SUBG] + l * 128);
.LBB0_257:
	s_setprio 0
	ds_bpermute_b32 v66, v163, v179
	v_lshlrev_b64 v[64:65], 11, v[166:167]
	s_mov_b32 s45, s25
	v_lshl_add_u64 v[64:65], s[10:11], 0, v[64:65]
	v_lshl_add_u64 v[64:65], v[64:65], 0, s[44:45]
	s_waitcnt lgkmcnt(0)
	v_add_f32_e32 v66, v179, v66
	v_div_scale_f32 v67, s[4:5], v66, v66, 1.0
	v_rcp_f32_e32 v68, v67
	v_div_scale_f32 v69, vcc, 1.0, v66, 1.0
	v_lshlrev_b32_e32 v160, 3, v185
	v_fma_f32 v70, -v67, v68, 1.0
	v_fmac_f32_e32 v68, v70, v68
	v_mul_f32_e32 v70, v69, v68
	v_fma_f32 v71, -v67, v70, v69
	v_fmac_f32_e32 v70, v71, v68
	v_fma_f32 v67, -v67, v70, v69
	v_div_fmas_f32 v67, v67, v68, v70
	v_div_fixup_f32 v66, v67, v66, 1.0
	v_pk_mul_f32 v[32:33], v[32:33], v[66:67] op_sel_hi:[1,0]
	v_pk_mul_f32 v[34:35], v[34:35], v[66:67] op_sel_hi:[1,0]
	v_lshl_add_u64 v[64:65], v[64:65], 0, v[160:161]
	v_cvt_pk_bf16_f32 v32, v32, v33
	v_cvt_pk_bf16_f32 v33, v34, v35
	global_store_dwordx2 v[64:65], v[32:33], off
	v_pk_mul_f32 v[32:33], v[36:37], v[66:67] op_sel_hi:[1,0]
	v_pk_mul_f32 v[34:35], v[38:39], v[66:67] op_sel_hi:[1,0]
	v_cvt_pk_bf16_f32 v32, v32, v33
	v_cvt_pk_bf16_f32 v33, v34, v35
	global_store_dwordx2 v[64:65], v[32:33], off offset:16
	v_pk_mul_f32 v[32:33], v[40:41], v[66:67] op_sel_hi:[1,0]
	v_pk_mul_f32 v[34:35], v[42:43], v[66:67] op_sel_hi:[1,0]
	v_cvt_pk_bf16_f32 v32, v32, v33
	v_cvt_pk_bf16_f32 v33, v34, v35
	global_store_dwordx2 v[64:65], v[32:33], off offset:32
	v_pk_mul_f32 v[32:33], v[44:45], v[66:67] op_sel_hi:[1,0]
	v_pk_mul_f32 v[34:35], v[46:47], v[66:67] op_sel_hi:[1,0]
	v_cvt_pk_bf16_f32 v32, v32, v33
	v_cvt_pk_bf16_f32 v33, v34, v35
	global_store_dwordx2 v[64:65], v[32:33], off offset:48
	v_pk_mul_f32 v[32:33], v[48:49], v[66:67] op_sel_hi:[1,0]
	v_pk_mul_f32 v[34:35], v[50:51], v[66:67] op_sel_hi:[1,0]
	v_pk_mul_f32 v[16:17], v[16:17], v[66:67] op_sel_hi:[1,0]
	v_pk_mul_f32 v[18:19], v[18:19], v[66:67] op_sel_hi:[1,0]
	v_pk_mul_f32 v[0:1], v[0:1], v[66:67] op_sel_hi:[1,0]
	v_pk_mul_f32 v[2:3], v[2:3], v[66:67] op_sel_hi:[1,0]
	v_cvt_pk_bf16_f32 v32, v32, v33
	v_cvt_pk_bf16_f32 v33, v34, v35
	v_cvt_pk_bf16_f32 v16, v16, v17
	v_cvt_pk_bf16_f32 v17, v18, v19
	v_cvt_pk_bf16_f32 v0, v0, v1
	v_cvt_pk_bf16_f32 v1, v2, v3
	global_store_dwordx2 v[64:65], v[32:33], off offset:64
	v_pk_mul_f32 v[32:33], v[52:53], v[66:67] op_sel_hi:[1,0]
	v_pk_mul_f32 v[34:35], v[54:55], v[66:67] op_sel_hi:[1,0]
	global_store_dwordx2 v[64:65], v[16:17], off offset:128
	v_pk_mul_f32 v[16:17], v[20:21], v[66:67] op_sel_hi:[1,0]
	v_pk_mul_f32 v[18:19], v[22:23], v[66:67] op_sel_hi:[1,0]
	global_store_dwordx2 v[64:65], v[0:1], off offset:192
	v_pk_mul_f32 v[0:1], v[4:5], v[66:67] op_sel_hi:[1,0]
	v_pk_mul_f32 v[2:3], v[6:7], v[66:67] op_sel_hi:[1,0]
	v_cvt_pk_bf16_f32 v32, v32, v33
	v_cvt_pk_bf16_f32 v33, v34, v35
	v_cvt_pk_bf16_f32 v16, v16, v17
	v_cvt_pk_bf16_f32 v17, v18, v19
	v_cvt_pk_bf16_f32 v0, v0, v1
	v_cvt_pk_bf16_f32 v1, v2, v3
	global_store_dwordx2 v[64:65], v[32:33], off offset:80
	v_pk_mul_f32 v[32:33], v[56:57], v[66:67] op_sel_hi:[1,0]
	v_pk_mul_f32 v[34:35], v[58:59], v[66:67] op_sel_hi:[1,0]
	global_store_dwordx2 v[64:65], v[16:17], off offset:144
	v_pk_mul_f32 v[16:17], v[24:25], v[66:67] op_sel_hi:[1,0]
	v_pk_mul_f32 v[18:19], v[26:27], v[66:67] op_sel_hi:[1,0]
	global_store_dwordx2 v[64:65], v[0:1], off offset:208
	v_pk_mul_f32 v[0:1], v[8:9], v[66:67] op_sel_hi:[1,0]
	v_pk_mul_f32 v[2:3], v[10:11], v[66:67] op_sel_hi:[1,0]
	v_cvt_pk_bf16_f32 v32, v32, v33
	v_cvt_pk_bf16_f32 v33, v34, v35
	v_cvt_pk_bf16_f32 v16, v16, v17
	v_cvt_pk_bf16_f32 v17, v18, v19
	v_cvt_pk_bf16_f32 v0, v0, v1
	v_cvt_pk_bf16_f32 v1, v2, v3
	global_store_dwordx2 v[64:65], v[32:33], off offset:96
	v_pk_mul_f32 v[32:33], v[60:61], v[66:67] op_sel_hi:[1,0]
	v_pk_mul_f32 v[34:35], v[62:63], v[66:67] op_sel_hi:[1,0]
	global_store_dwordx2 v[64:65], v[16:17], off offset:160
	v_pk_mul_f32 v[16:17], v[28:29], v[66:67] op_sel_hi:[1,0]
	v_pk_mul_f32 v[18:19], v[30:31], v[66:67] op_sel_hi:[1,0]
	global_store_dwordx2 v[64:65], v[0:1], off offset:224
	v_pk_mul_f32 v[0:1], v[12:13], v[66:67] op_sel_hi:[1,0]
	v_pk_mul_f32 v[2:3], v[14:15], v[66:67] op_sel_hi:[1,0]
	v_cvt_pk_bf16_f32 v32, v32, v33
	v_cvt_pk_bf16_f32 v33, v34, v35
	v_cvt_pk_bf16_f32 v16, v16, v17
	v_cvt_pk_bf16_f32 v17, v18, v19
	v_cvt_pk_bf16_f32 v0, v0, v1
	v_cvt_pk_bf16_f32 v1, v2, v3
	global_store_dwordx2 v[64:65], v[32:33], off offset:112
	global_store_dwordx2 v[64:65], v[16:17], off offset:176
	global_store_dwordx2 v[64:65], v[0:1], off offset:240
	s_barrier
	s_load_dwordx2 s[4:5], s[64:65], 0x58
	s_mov_b32 s75, 0
	s_waitcnt lgkmcnt(0)
	s_add_u32 s6, s4, s12
	s_addc_u32 s7, s5, s13
	s_add_u32 s8, s56, s44
	s_addc_u32 s9, s57, 0
	s_or_b32 s52, s0, 16
	s_xor_b32 s53, s0, 31
	s_lshl_b64 s[4:5], s[42:43], 20
	s_add_u32 s42, s76, s4
	s_addc_u32 s43, s77, s5
	s_add_u32 s44, s68, s44
	s_addc_u32 s45, s69, 0
	s_branch .LBB0_259

; #define GLOAD(K0, K1, V0, V1, kvt) do { const size_t ko_ = (size_t)(kvt) * 64 * QKVW; const int vo_ = (kvt) * 64; \
;         K0 = *(const u32x4*)(kg0 + ko_); K1 = *(const u32x4*)(kg1 + ko_); V0 = *(const u32x4*)(vg0 + vo_); V1 = *(const u32x4*)(vg1 + vo_); } while (0)
; #define STEP_LEAD(kvt, kslot, vso) do { f32x16 p0, p1; bool act, lval; \
;             QK_TILE(kvt, kslot); \
;             if (act) { SOFTMAX_HALF(p0, pa0, pb0); PV_HALF(vso, 0, pa0, pb0); SOFTMAX_HALF(p1, pa1, pb1); PV_HALF(vso, 2, pa1, pb1); } \
;         } while (0)
; #define STEP_TRAIL(kvt, kslot, vso) do { f32x16 p0, p1; bool act, lval; \
;             if (actp) { PV_HALF(vsp, 0, pa0, pb0); PV_HALF(vsp, 2, pa1, pb1); } \
;             QK_TILE(kvt, kslot); \
;             if (act) { SOFTMAX_FULL(p0, p1, pa0, pb0, pa1, pb1); } \
;             actp = act; vsp = (vso); \
;         } while (0)
; template <int MODE> ...
;     ...
;     { const bf16_t* qp = QKV + (tokbase + qpos) * QKVW + qcol + hi * 8;
; #pragma unroll
;       for (int dk = 0; dk < NDK; ++dk) qf[dk] = *(const bf16x8*)(qp + dk * 16); }
;     float m = NEG, l = 0.f;
;     f32x16 o[4];
; #pragma unroll
;     for (int i = 0; i < 4; ++i)
; #pragma unroll
;         for (int r = 0; r < 16; ++r) o[i][r] = 0.f;
;     u32x4 kr0, kr1, vr0, vr1;
;     const int idA = tid, idB = tid + 512;
;     const bf16_t* kg0 = QKV + (tokbase + (idA >> 4)) * QKVW + kcol + (idA & 15) * 8;
;     const bf16_t* kg1 = QKV + (tokbase + (idB >> 4)) * QKVW + kcol + (idB & 15) * 8;
;     const bf16_t* vg0 = VTb + (size_t)(idA >> 3) * SEQ + (idA & 7) * 8;
;     const bf16_t* vg1 = VTb + (size_t)(idB >> 3) * SEQ + (idB & 7) * 8;
;     const int kl0 = (idA >> 4) * KP + (idA & 15) * 16, kl1 = (idB >> 4) * KP + (idB & 15) * 16;
;     const int vl0 = VRING + (idA >> 3) * VP + ((idA & 7) >> 1) * 32 + (idA & 1) * 8, vl1 = VRING + (idB >> 3) * VP + ((idB & 7) >> 1) * 32 + (idB & 1) * 8;
;     ...
;     GLOAD(kr0, kr1, vr0, vr1, TILE_AT(0));
;     if (trailing) {
;         TILE_LOOP(STEP_TRAIL);
;         if (actp) { PV_HALF(vsp, 0, pa0, pb0); PV_HALF(vsp, 2, pa1, pb1); }
;     } else {
;         TILE_LOOP(STEP_LEAD);
.LBB0_264:
	v_mov_b32_e32 v14, v202
	s_lshl_b32 s28, s29, 7
	v_readfirstlane_b32 s4, v14
	s_ashr_i32 s79, s4, 2
	s_andn2_b32 s79, s79, 31
	v_and_b32_e32 v167, 31, v14
	s_add_i32 s80, s79, s28
	s_ashr_i32 s54, s4, 6
	s_waitcnt vmcnt(16)
	v_or_b32_e32 v146, s80, v167
	s_and_b32 s78, s54, 1
	v_ashrrev_i32_e32 v147, 31, v146
	s_lshl_b32 s55, s78, 6
	v_lshl_add_u64 v[144:145], s[14:15], 0, v[146:147]
	v_mov_b64_e32 v[0:1], s[68:69]
	s_or_b32 s24, s55, s1
	v_mad_u64_u32 v[0:1], s[4:5], v144, s35, v[0:1]
	v_bfe_u32 v64, v14, 5, 1
	v_mad_i32_i24 v1, v145, s35, v1
	s_lshl_b32 s24, s24, 1
	v_lshl_add_u64 v[0:1], v[0:1], 0, s[24:25]
	v_lshlrev_b32_e32 v160, 4, v64
	v_lshl_add_u64 v[0:1], v[0:1], 0, v[160:161]
	global_load_dwordx4 v[96:99], v[0:1], off
	global_load_dwordx4 v[100:103], v[0:1], off offset:32
	global_load_dwordx4 v[104:107], v[0:1], off offset:64
	global_load_dwordx4 v[108:111], v[0:1], off offset:96
	v_ashrrev_i32_e32 v0, 4, v14
	v_ashrrev_i32_e32 v1, 31, v0
	v_lshl_add_u64 v[2:3], s[14:15], 0, v[0:1]
	v_mov_b64_e32 v[4:5], s[44:45]
	v_mad_u64_u32 v[6:7], s[4:5], v2, s35, v[4:5]
	v_lshlrev_b32_e32 v1, 4, v14
	v_add_u32_e32 v12, 0x200, v14
	v_mad_i32_i24 v7, v3, s35, v7
	v_and_b32_e32 v2, 0xf0, v1
	v_mov_b32_e32 v3, v161
	v_lshl_add_u64 v[148:149], v[6:7], 0, v[2:3]
	v_ashrrev_i32_e32 v6, 4, v12
	v_ashrrev_i32_e32 v7, 31, v6
	v_lshl_add_u64 v[8:9], s[14:15], 0, v[6:7]
	v_mad_u64_u32 v[4:5], s[4:5], v8, s35, v[4:5]
	v_mad_i32_i24 v5, v9, s35, v5
	v_lshl_add_u64 v[150:151], v[4:5], 0, v[2:3]
	v_ashrrev_i32_e32 v4, 3, v14
	v_ashrrev_i32_e32 v5, 31, v4
	v_lshlrev_b64 v[8:9], 13, v[4:5]
	v_and_b32_e32 v3, 7, v14
	v_lshl_add_u64 v[8:9], s[42:43], 0, v[8:9]
	v_lshlrev_b32_e32 v10, 4, v3
	v_mov_b32_e32 v11, v161
	v_lshl_add_u64 v[152:153], v[8:9], 0, v[10:11]
	v_ashrrev_i32_e32 v8, 3, v12
	v_ashrrev_i32_e32 v9, 31, v8
	v_lshlrev_b64 v[12:13], 13, v[8:9]
	v_lshl_add_u64 v[12:13], s[42:43], 0, v[12:13]
	v_lshl_add_u64 v[154:155], v[12:13], 0, v[10:11]
	global_load_dwordx4 v[116:119], v[148:149], off offset:2048
	global_load_dwordx4 v[120:123], v[150:151], off offset:2048
	global_load_dwordx4 v[124:127], v[152:153], off
	global_load_dwordx4 v[112:115], v[154:155], off
	v_lshlrev_b32_e32 v3, 3, v64
	v_mad_u64_u32 v[156:157], s[4:5], v0, s49, v[2:3]
	v_mad_u64_u32 v[158:159], s[4:5], v6, s49, v[2:3]
	v_lshlrev_b32_e32 v2, 3, v14
	s_lshl_b32 s24, s29, 1
	v_and_b32_e32 v1, 0x60, v1
	v_and_b32_e32 v2, 8, v2
	s_add_i32 s81, s24, 2
	v_mul_lo_u32 v0, v4, s23
	v_mul_lo_u32 v4, v8, s23
	v_or_b32_e32 v5, v1, v2
	s_or_b32 s86, s24, 1
	v_or_b32_e32 v3, s55, v3
	s_cmp_gt_i32 s54, 3
	s_mov_b64 s[4:5], -1
	v_mul_u32_u24_e32 v159, 0x110, v167
	v_mul_u32_u24_e32 v157, 0x90, v167
	v_add3_u32 v169, v0, v2, v1
	v_add_u32_e32 v170, v5, v4
	v_lshlrev_b32_e32 v171, 1, v3
	v_lshlrev_b32_e32 v147, 2, v64
	s_cbranch_scc1 .LBB0_278
	v_mov_b32_e32 v14, v161
	v_mov_b32_e32 v15, v161
	v_mov_b32_e32 v0, v161
	v_mov_b32_e32 v1, v161
	v_mov_b32_e32 v2, v161
	v_mov_b32_e32 v3, v161
	v_mov_b32_e32 v4, v161
	v_mov_b32_e32 v5, v161
	v_mov_b32_e32 v6, v161
	v_mov_b32_e32 v7, v161
	v_mov_b32_e32 v8, v161
	v_mov_b32_e32 v9, v161
	v_mov_b32_e32 v10, v161
	v_mov_b32_e32 v11, v161
	v_mov_b32_e32 v12, v161
	v_mov_b32_e32 v13, v161
	v_mov_b64_e32 v[30:31], v[14:15]
	v_mov_b64_e32 v[46:47], v[14:15]
	v_mov_b64_e32 v[62:63], v[14:15]
	s_waitcnt vmcnt(3)
	v_mov_b64_e32 v[134:135], v[118:119]
	s_waitcnt vmcnt(2)
	v_mov_b64_e32 v[138:139], v[122:123]
	s_waitcnt vmcnt(1)
	v_mov_b64_e32 v[142:143], v[126:127]
	s_waitcnt vmcnt(0)
	v_mov_b64_e32 v[130:131], v[114:115]
	s_or_b32 s4, s80, 31
	s_mov_b32 s5, 1
	v_lshlrev_b32_e32 v166, 2, v64
	s_add_i32 s29, s28, 0x80
	s_mov_b32 s54, 0
	v_mov_b32_e32 v172, 0
	v_mov_b32_e32 v173, 0xf149f2ca
	v_mov_b64_e32 v[28:29], v[12:13]
	v_mov_b64_e32 v[26:27], v[10:11]
	v_mov_b64_e32 v[24:25], v[8:9]
	v_mov_b64_e32 v[22:23], v[6:7]
	v_mov_b64_e32 v[20:21], v[4:5]
	v_mov_b64_e32 v[18:19], v[2:3]
	v_mov_b64_e32 v[16:17], v[0:1]
	v_mov_b64_e32 v[44:45], v[12:13]
	v_mov_b64_e32 v[42:43], v[10:11]
	v_mov_b64_e32 v[40:41], v[8:9]
	v_mov_b64_e32 v[38:39], v[6:7]
	v_mov_b64_e32 v[36:37], v[4:5]
	v_mov_b64_e32 v[34:35], v[2:3]
	v_mov_b64_e32 v[32:33], v[0:1]
	v_mov_b64_e32 v[60:61], v[12:13]
	v_mov_b64_e32 v[58:59], v[10:11]
	v_mov_b64_e32 v[56:57], v[8:9]
	v_mov_b64_e32 v[54:55], v[6:7]
	v_mov_b64_e32 v[52:53], v[4:5]
	v_mov_b64_e32 v[50:51], v[2:3]
	v_mov_b64_e32 v[48:49], v[0:1]
	v_mov_b64_e32 v[132:133], v[116:117]
	v_mov_b64_e32 v[136:137], v[120:121]
	v_mov_b64_e32 v[140:141], v[124:125]
	v_mov_b64_e32 v[128:129], v[112:113]
	s_mov_b32 s55, 0
	s_mov_b32 s87, 0
	s_setprio 1
	s_branch .LBB0_269

; #define LAS __attribute__((address_space(3)))
; __device__ __forceinline__ unsigned pk2(float lo, float hi) { const f32x2 v = {lo, hi}; const bf16x2_cv b = __builtin_convertvector(v, bf16x2_cv); return __builtin_bit_cast(unsigned, b); }
; #define LAS __attribute__((address_space(3)))
; __device__ __forceinline__ unsigned pk2(float lo, float hi) { return f2bf(lo) | (f2bf(hi) << 16); }
; template <int MODE> ...
;     ...
;     l += __shfl_xor(l, 32);
;     const float inv = 1.0f / l;
;     if (MODE == 1) {
;         bf16_t* yp = Y + (tokbase + qpos) * 1024 + h * 128 + 4 * hi;
; #pragma unroll
;         for (int bl = 0; bl < 4; ++bl)
; #pragma unroll
;             for (int g = 0; g < 4; ++g) {
;                 u32x2 w; w.x = pk2(o[bl][4 * g] * inv, o[bl][4 * g + 1] * inv); w.y = pk2(o[bl][4 * g + 2] * inv, o[bl][4 * g + 3] * inv);
;                 *(u32x2*)(yp + bl * 32 + 8 * g) = w;
;             }
;         __syncthreads();
;     } else {
;         __syncthreads();
;         LAS float* cb = (LAS float*)lds + (slab * 32 + r32) * 132 + 4 * hi;
;         if (cmap == 1) {
; #pragma unroll
;             for (int bl = 0; bl < 4; ++bl)
; #pragma unroll
;                 for (int g = 0; g < 4; ++g)
;                     *(LAS f32x4*)(cb + bl * 32 + 8 * g) = (f32x4){o[bl][4 * g] * inv, o[bl][4 * g + 1] * inv, o[bl][4 * g + 2] * inv, o[bl][4 * g + 3] * inv};
;         }
.LBB0_294:
	s_setprio 0
	ds_bpermute_b32 v64, v163, v172
	s_cmp_eq_u32 s78, 0
	s_waitcnt lgkmcnt(0)
	s_barrier
	v_add_f32_e32 v64, v172, v64
	v_div_scale_f32 v65, s[4:5], v64, v64, 1.0
	v_rcp_f32_e32 v66, v65
	v_div_scale_f32 v67, vcc, 1.0, v64, 1.0
	s_movk_i32 s4, 0x210
	v_fma_f32 v68, -v65, v66, 1.0
	v_fmac_f32_e32 v66, v68, v66
	v_mul_f32_e32 v68, v67, v66
	v_fma_f32 v69, -v65, v68, v67
	v_fmac_f32_e32 v68, v69, v66
	v_fma_f32 v65, -v65, v68, v67
	v_div_fmas_f32 v65, v65, v66, v68
	v_div_fixup_f32 v72, v65, v64, 1.0
	v_or_b32_e32 v64, s79, v167
	v_mul_lo_u32 v64, v64, s4
	v_lshlrev_b32_e32 v65, 2, v166
	s_cselect_b64 s[4:5], -1, 0
	v_add3_u32 v64, 0, v64, v65
	s_and_b64 vcc, exec, s[4:5]
	s_cbranch_vccnz .LBB0_296
	v_pk_mul_f32 v[66:67], v[48:49], v[72:73] op_sel_hi:[1,0]
	v_pk_mul_f32 v[68:69], v[50:51], v[72:73] op_sel_hi:[1,0]
	ds_write_b128 v64, v[66:69]
	v_pk_mul_f32 v[66:67], v[52:53], v[72:73] op_sel_hi:[1,0]
	v_pk_mul_f32 v[68:69], v[54:55], v[72:73] op_sel_hi:[1,0]
	ds_write_b128 v64, v[66:69] offset:32
	v_pk_mul_f32 v[66:67], v[56:57], v[72:73] op_sel_hi:[1,0]
	v_pk_mul_f32 v[68:69], v[58:59], v[72:73] op_sel_hi:[1,0]
	ds_write_b128 v64, v[66:69] offset:64
	v_pk_mul_f32 v[66:67], v[60:61], v[72:73] op_sel_hi:[1,0]
	v_pk_mul_f32 v[68:69], v[62:63], v[72:73] op_sel_hi:[1,0]
	ds_write_b128 v64, v[66:69] offset:96
	v_pk_mul_f32 v[66:67], v[32:33], v[72:73] op_sel_hi:[1,0]
	v_pk_mul_f32 v[68:69], v[34:35], v[72:73] op_sel_hi:[1,0]
	ds_write_b128 v64, v[66:69] offset:128
	v_pk_mul_f32 v[66:67], v[36:37], v[72:73] op_sel_hi:[1,0]
	v_pk_mul_f32 v[68:69], v[38:39], v[72:73] op_sel_hi:[1,0]
	ds_write_b128 v64, v[66:69] offset:160
	v_pk_mul_f32 v[66:67], v[40:41], v[72:73] op_sel_hi:[1,0]
	v_pk_mul_f32 v[68:69], v[42:43], v[72:73] op_sel_hi:[1,0]
	ds_write_b128 v64, v[66:69] offset:192
	v_pk_mul_f32 v[66:67], v[44:45], v[72:73] op_sel_hi:[1,0]
	v_pk_mul_f32 v[68:69], v[46:47], v[72:73] op_sel_hi:[1,0]
	ds_write_b128 v64, v[66:69] offset:224
	v_pk_mul_f32 v[66:67], v[16:17], v[72:73] op_sel_hi:[1,0]
	v_pk_mul_f32 v[68:69], v[18:19], v[72:73] op_sel_hi:[1,0]
	ds_write_b128 v64, v[66:69] offset:256
	v_pk_mul_f32 v[66:67], v[20:21], v[72:73] op_sel_hi:[1,0]
	v_pk_mul_f32 v[68:69], v[22:23], v[72:73] op_sel_hi:[1,0]
	ds_write_b128 v64, v[66:69] offset:288
	v_pk_mul_f32 v[66:67], v[24:25], v[72:73] op_sel_hi:[1,0]
	v_pk_mul_f32 v[68:69], v[26:27], v[72:73] op_sel_hi:[1,0]
	ds_write_b128 v64, v[66:69] offset:320
	v_pk_mul_f32 v[66:67], v[28:29], v[72:73] op_sel_hi:[1,0]
	v_pk_mul_f32 v[68:69], v[30:31], v[72:73] op_sel_hi:[1,0]
	ds_write_b128 v64, v[66:69] offset:352
	v_pk_mul_f32 v[66:67], v[0:1], v[72:73] op_sel_hi:[1,0]
	v_pk_mul_f32 v[68:69], v[2:3], v[72:73] op_sel_hi:[1,0]
	ds_write_b128 v64, v[66:69] offset:384
	v_pk_mul_f32 v[66:67], v[4:5], v[72:73] op_sel_hi:[1,0]
	v_pk_mul_f32 v[68:69], v[6:7], v[72:73] op_sel_hi:[1,0]
	ds_write_b128 v64, v[66:69] offset:416
	v_pk_mul_f32 v[66:67], v[8:9], v[72:73] op_sel_hi:[1,0]
	v_pk_mul_f32 v[68:69], v[10:11], v[72:73] op_sel_hi:[1,0]
	ds_write_b128 v64, v[66:69] offset:448
	v_pk_mul_f32 v[66:67], v[12:13], v[72:73] op_sel_hi:[1,0]
	v_pk_mul_f32 v[68:69], v[14:15], v[72:73] op_sel_hi:[1,0]
	ds_write_b128 v64, v[66:69] offset:480
